# P0 x rows: rows_x0<4> loop as hand-scheduled two-set pipeline (on top of lean P3/P10/P13 + barrier poll change)
# speedup vs baseline: 1.0032x; 1.0032x over previous
; __device__ __forceinline__ const float* xrow_ptr(const Ctx& C, int row) { return row < MPROMPT ? C.in(0) + (size_t)row * DM : C.in(1) + (size_t)(row - MPROMPT) * DM; }
; __device__ __forceinline__ float ssq4(v4f v) { return (v.x * v.x + v.y * v.y) + (v.z * v.z + v.w * v.w); }
; template <int R>
; __device__ __forceinline__ void rows_x0(const Ctx& C, int m0, int stride, int mx, int lane) {
;     v4f v[R][4]; float ss[R]; int mr[R]; bool ok[R];
; #pragma unroll
;     for (int r = 0; r < R; ++r) { mr[r] = (r == 4) ? mx : m0 + r * stride; ok[r] = (r == 4) ? (mx < M) : (mr[r] < MPROMPT); const float* x = xrow_ptr(C, ok[r] ? mr[r] : 0);
; #pragma unroll
;         for (int j = 0; j < 4; ++j) v[r][j] = __builtin_nontemporal_load((const v4f*)(x + 4 * lane + 256 * j)); }
;     bf16* XN = C.XN();
; #pragma unroll
;     for (int r = 0; r < R; ++r) { float s = 0.f;
; #pragma unroll
;         for (int j = 0; j < 4; ++j) s += ssq4(v[r][j]);
;         ss[r] = s; }
;     float* rs = C.RS();
; #pragma unroll
;     for (int r = 0; r < R; ++r) ss[r] = wave_sum(ss[r]) * (1.f / DM) + EPS;
; __device__ __forceinline__ void p0_prologue(const Ctx& C, LAS unsigned char* lds, int wave, int lane, int tid) {
;     ...
;     { const int nit = (MPROMPT + 4 * NGW - 1) / (4 * NGW);
;       for (int it = 0; it < nit - 1; ++it) rows_x0<4>(C, gw + 4 * it * NGW, NGW, M, lane);
.LBB0_60:
	s_lshl_b32 s45, s44, 5
	s_abs_i32 s0, s45
	v_cvt_f32_u32_e32 v0, s0
	s_ashr_i32 s62, s3, 6
	s_sub_i32 s3, 0, s0
	s_lshl_b32 s1, s33, 3
	v_rcp_iflag_f32_e32 v0, v0
	s_add_i32 s40, s62, s1
	v_writelane_b32 v232, s1, 0
	s_add_i32 s1, s45, 0x7fff
	v_mul_f32_e32 v0, 0x4f7ffffe, v0
	v_cvt_u32_f32_e32 v0, v0
	s_xor_b32 s2, s1, s45
	s_abs_i32 s1, s1
	s_lshl_b32 s46, s44, 3
	v_readfirstlane_b32 s4, v0
	s_mul_i32 s3, s3, s4
	s_mul_hi_u32 s3, s4, s3
	s_add_i32 s4, s4, s3
	s_mul_hi_u32 s3, s1, s4
	s_mul_i32 s4, s3, s0
	s_sub_i32 s1, s1, s4
	s_ashr_i32 s2, s2, 31
	s_add_i32 s4, s3, 1
	s_sub_i32 s5, s1, s0
	s_cmp_ge_u32 s1, s0
	s_cselect_b32 s3, s4, s3
	s_cselect_b32 s1, s5, s1
	s_add_i32 s4, s3, 1
	s_cmp_ge_u32 s1, s0
	s_cselect_b32 s0, s4, s3
	s_xor_b32 s0, s0, s2
	s_sub_i32 s0, s0, s2
	s_add_i32 s3, s0, -1
	s_cmp_gt_i32 s0, 1
	v_and_b32_e32 v86, 63, v84
	s_cselect_b64 s[4:5], -1, 0
	v_writelane_b32 v232, s4, 1
	s_lshl_b32 s2, s44, 4
	v_lshlrev_b32_e32 v0, 2, v86
	v_writelane_b32 v232, s5, 2
	s_cmp_lt_i32 s0, 2
	v_mov_b32_e32 v81, 0
	s_mul_i32 s1, s44, 24
	v_cmp_ne_u32_e64 s[4:5], 0, v86
	v_lshlrev_b32_e32 v85, 2, v0
	v_mbcnt_lo_u32_b32 v82, -1, 0
	v_lshlrev_b32_e32 v80, 1, v0
	s_cbranch_scc1 .LBB0_79
	v_mbcnt_hi_u32_b32 v66, -1, v82
	v_and_b32_e32 v0, 64, v66
	v_add_u32_e32 v67, 64, v0
	v_xor_b32_e32 v68, 1, v66
	v_xor_b32_e32 v69, 2, v66
	v_xor_b32_e32 v70, 4, v66
	v_xor_b32_e32 v71, 8, v66
	v_xor_b32_e32 v72, 16, v66
	v_xor_b32_e32 v73, 32, v66
	v_mov_b32_e32 v74, 0x358637bd
	s_mov_b64 s[8:9], 0x3000000
	s_mov_b32 s38, 0x800000
	s_mov_b32 s39, 0xf800000
	v_mov_b32_e32 v75, 0x260
	s_mov_b32 s12, s40
	s_mov_b32 s41, s3
	s_load_dwordx2 s[98:99], s[80:81], 0x110
	s_load_dwordx2 s[100:101], s[80:81], 0x0
	v_xor_b32_e32 v71, 16, v86
	v_xor_b32_e32 v72, 32, v86
	v_lshlrev_b32_e32 v71, 2, v71
	v_lshlrev_b32_e32 v72, 2, v72
	s_lshl_b32 vcc_lo, s40, 12
	v_add_u32_e32 v130, vcc_lo, v85
	s_lshl_b32 vcc_lo, s40, 11
	v_add_u32_e32 v131, vcc_lo, v80
	v_add_u32_e32 v131, 0x3000000, v131
	s_lshl_b32 vcc_lo, s40, 2
	v_mov_b32_e32 v132, 0x2a80000
	v_add_u32_e32 v132, vcc_lo, v132
	v_mov_b32_e32 v70, 0x358637bd
	s_waitcnt lgkmcnt(0)
	global_load_dwordx4 v[0:3], v130, s[100:101] nt
	global_load_dwordx4 v[4:7], v130, s[100:101] offset:1024 nt
	global_load_dwordx4 v[8:11], v130, s[100:101] offset:2048 nt
	global_load_dwordx4 v[12:15], v130, s[100:101] offset:3072 nt
	v_add_u32_e32 v130, 0x800000, v130
	global_load_dwordx4 v[16:19], v130, s[100:101] nt
	global_load_dwordx4 v[20:23], v130, s[100:101] offset:1024 nt
	global_load_dwordx4 v[24:27], v130, s[100:101] offset:2048 nt
	global_load_dwordx4 v[28:31], v130, s[100:101] offset:3072 nt
	v_add_u32_e32 v130, 0x800000, v130
	global_load_dwordx4 v[32:35], v130, s[100:101] nt
	global_load_dwordx4 v[36:39], v130, s[100:101] offset:1024 nt
	global_load_dwordx4 v[40:43], v130, s[100:101] offset:2048 nt
	global_load_dwordx4 v[44:47], v130, s[100:101] offset:3072 nt
	v_add_u32_e32 v130, 0x800000, v130
	global_load_dwordx4 v[48:51], v130, s[100:101] nt
	global_load_dwordx4 v[52:55], v130, s[100:101] offset:1024 nt
	global_load_dwordx4 v[56:59], v130, s[100:101] offset:2048 nt
	global_load_dwordx4 v[60:63], v130, s[100:101] offset:3072 nt
	v_add_u32_e32 v130, 0x800000, v130
	s_waitcnt vmcnt(12)
	v_pk_mul_f32 v[64:65], v[0:1], v[0:1]
	v_pk_fma_f32 v[64:65], v[2:3], v[2:3], v[64:65]
	v_pk_fma_f32 v[64:65], v[4:5], v[4:5], v[64:65]
	v_pk_fma_f32 v[64:65], v[6:7], v[6:7], v[64:65]
	v_pk_fma_f32 v[64:65], v[8:9], v[8:9], v[64:65]
	v_pk_fma_f32 v[64:65], v[10:11], v[10:11], v[64:65]
	v_pk_fma_f32 v[64:65], v[12:13], v[12:13], v[64:65]
	v_pk_fma_f32 v[64:65], v[14:15], v[14:15], v[64:65]
	s_nop 0
	v_add_f32_e32 v64, v64, v65
	s_waitcnt vmcnt(8)
	v_pk_mul_f32 v[66:67], v[16:17], v[16:17]
	v_pk_fma_f32 v[66:67], v[18:19], v[18:19], v[66:67]
	v_pk_fma_f32 v[66:67], v[20:21], v[20:21], v[66:67]
	v_pk_fma_f32 v[66:67], v[22:23], v[22:23], v[66:67]
	v_pk_fma_f32 v[66:67], v[24:25], v[24:25], v[66:67]
	v_pk_fma_f32 v[66:67], v[26:27], v[26:27], v[66:67]
	v_pk_fma_f32 v[66:67], v[28:29], v[28:29], v[66:67]
	v_pk_fma_f32 v[66:67], v[30:31], v[30:31], v[66:67]
	s_nop 0
	v_add_f32_e32 v66, v66, v67
	s_nop 1
	v_add_f32_dpp v64, v64, v64 quad_perm:[1,0,3,2] row_mask:0xf bank_mask:0xf
	v_add_f32_dpp v66, v66, v66 quad_perm:[1,0,3,2] row_mask:0xf bank_mask:0xf
	s_nop 0
	v_add_f32_dpp v64, v64, v64 quad_perm:[2,3,0,1] row_mask:0xf bank_mask:0xf
	v_add_f32_dpp v66, v66, v66 quad_perm:[2,3,0,1] row_mask:0xf bank_mask:0xf
	s_nop 0
	v_add_f32_dpp v64, v64, v64 row_half_mirror row_mask:0xf bank_mask:0xf
	v_add_f32_dpp v66, v66, v66 row_half_mirror row_mask:0xf bank_mask:0xf
	s_nop 0
	v_add_f32_dpp v64, v64, v64 row_mirror row_mask:0xf bank_mask:0xf
	v_add_f32_dpp v66, v66, v66 row_mirror row_mask:0xf bank_mask:0xf
	s_nop 0
	ds_bpermute_b32 v68, v71, v64
	ds_bpermute_b32 v69, v71, v66
	s_waitcnt lgkmcnt(0)
	v_add_f32_e32 v64, v64, v68
	v_add_f32_e32 v66, v66, v69
	ds_bpermute_b32 v68, v72, v64
	ds_bpermute_b32 v69, v72, v66
	s_waitcnt lgkmcnt(0)
; __device__ __forceinline__ const float* xrow_ptr(const Ctx& C, int row) { return row < MPROMPT ? C.in(0) + (size_t)row * DM : C.in(1) + (size_t)(row - MPROMPT) * DM; }
; __device__ __forceinline__ void st4_bf16(bf16* p, v4f o) { v2u w; w.x = cvt_pk_nv(o.x, o.y); w.y = cvt_pk_nv(o.z, o.w); *(v2u*)p = w; }
; __device__ __forceinline__ float ssq4(v4f v) { return (v.x * v.x + v.y * v.y) + (v.z * v.z + v.w * v.w); }
; template <int R>
; __device__ __forceinline__ void rows_x0(const Ctx& C, int m0, int stride, int mx, int lane) {
;     v4f v[R][4]; float ss[R]; int mr[R]; bool ok[R];
; #pragma unroll
;     for (int r = 0; r < R; ++r) { mr[r] = (r == 4) ? mx : m0 + r * stride; ok[r] = (r == 4) ? (mx < M) : (mr[r] < MPROMPT); const float* x = xrow_ptr(C, ok[r] ? mr[r] : 0);
; #pragma unroll
;         for (int j = 0; j < 4; ++j) v[r][j] = __builtin_nontemporal_load((const v4f*)(x + 4 * lane + 256 * j)); }
;     bf16* XN = C.XN();
; #pragma unroll
;     for (int r = 0; r < R; ++r) { float s = 0.f;
; #pragma unroll
;         for (int j = 0; j < 4; ++j) s += ssq4(v[r][j]);
;         ss[r] = s; }
;     float* rs = C.RS();
; #pragma unroll
;     for (int r = 0; r < R; ++r) ss[r] = wave_sum(ss[r]) * (1.f / DM) + EPS;
; #pragma unroll
;     for (int r = 0; r < R; ++r) { const float rstd = rsqrtf(ss[r]);
; #pragma unroll
;         for (int j = 0; j < 4; ++j) if (ok[r]) st4_bf16(XN + (size_t)mr[r] * DM + 4 * lane + 256 * j, v[r][j] * rstd);
;         if (lane == 0 && ok[r]) rs[mr[r]] = sqrtf(ss[r]); }
	v_add_f32_e32 v64, v64, v68
	v_add_f32_e32 v66, v66, v69
	v_fmamk_f32 v124, v64, 0x3a800000, v70
	v_fmamk_f32 v127, v66, 0x3a800000, v70
	s_nop 0
	v_rsq_f32_e32 v64, v124
	v_rsq_f32_e32 v66, v127
	v_sqrt_f32_e32 v125, v124
	v_sqrt_f32_e32 v128, v127
	s_nop 1
	v_pk_mul_f32 v[116:117], v[0:1], v[64:65] op_sel_hi:[1,0]
	v_cvt_pk_bf16_f32 v100, v116, v117
	v_pk_mul_f32 v[118:119], v[2:3], v[64:65] op_sel_hi:[1,0]
	v_cvt_pk_bf16_f32 v101, v118, v119
	v_pk_mul_f32 v[120:121], v[4:5], v[64:65] op_sel_hi:[1,0]
	v_cvt_pk_bf16_f32 v102, v120, v121
	v_pk_mul_f32 v[122:123], v[6:7], v[64:65] op_sel_hi:[1,0]
	v_cvt_pk_bf16_f32 v103, v122, v123
	v_pk_mul_f32 v[116:117], v[8:9], v[64:65] op_sel_hi:[1,0]
	v_cvt_pk_bf16_f32 v104, v116, v117
	v_pk_mul_f32 v[118:119], v[10:11], v[64:65] op_sel_hi:[1,0]
	v_cvt_pk_bf16_f32 v105, v118, v119
	v_pk_mul_f32 v[120:121], v[12:13], v[64:65] op_sel_hi:[1,0]
	v_cvt_pk_bf16_f32 v106, v120, v121
	v_pk_mul_f32 v[122:123], v[14:15], v[64:65] op_sel_hi:[1,0]
	v_cvt_pk_bf16_f32 v107, v122, v123
	global_store_dwordx2 v131, v[100:101], s[98:99]
	global_store_dwordx2 v131, v[102:103], s[98:99] offset:512
	global_store_dwordx2 v131, v[104:105], s[98:99] offset:1024
	global_store_dwordx2 v131, v[106:107], s[98:99] offset:1536
	v_add_u32_e32 v131, 0x400000, v131
	v_pk_mul_f32 v[116:117], v[16:17], v[66:67] op_sel_hi:[1,0]
	v_cvt_pk_bf16_f32 v108, v116, v117
	v_pk_mul_f32 v[118:119], v[18:19], v[66:67] op_sel_hi:[1,0]
	v_cvt_pk_bf16_f32 v109, v118, v119
	v_pk_mul_f32 v[120:121], v[20:21], v[66:67] op_sel_hi:[1,0]
	v_cvt_pk_bf16_f32 v110, v120, v121
	v_pk_mul_f32 v[122:123], v[22:23], v[66:67] op_sel_hi:[1,0]
	v_cvt_pk_bf16_f32 v111, v122, v123
	v_pk_mul_f32 v[116:117], v[24:25], v[66:67] op_sel_hi:[1,0]
	v_cvt_pk_bf16_f32 v112, v116, v117
	v_pk_mul_f32 v[118:119], v[26:27], v[66:67] op_sel_hi:[1,0]
	v_cvt_pk_bf16_f32 v113, v118, v119
	v_pk_mul_f32 v[120:121], v[28:29], v[66:67] op_sel_hi:[1,0]
	v_cvt_pk_bf16_f32 v114, v120, v121
	v_pk_mul_f32 v[122:123], v[30:31], v[66:67] op_sel_hi:[1,0]
	v_cvt_pk_bf16_f32 v115, v122, v123
	global_store_dwordx2 v131, v[108:109], s[98:99]
	global_store_dwordx2 v131, v[110:111], s[98:99] offset:512
	global_store_dwordx2 v131, v[112:113], s[98:99] offset:1024
	global_store_dwordx2 v131, v[114:115], s[98:99] offset:1536
	v_add_u32_e32 v131, 0x400000, v131
	v_add_u32_e32 v126, -1, v125
	v_fma_f32 v116, -v126, v125, v124
	v_cmp_ge_f32_e32 vcc, 0, v116
	v_add_u32_e32 v117, 1, v125
	v_cndmask_b32_e32 v126, v125, v126, vcc
	v_fma_f32 v116, -v117, v125, v124
	v_cmp_lt_f32_e32 vcc, 0, v116
	s_nop 1
	v_cndmask_b32_e32 v125, v126, v117, vcc
	v_add_u32_e32 v129, -1, v128
	v_fma_f32 v118, -v129, v128, v127
	v_cmp_ge_f32_e32 vcc, 0, v118
	v_add_u32_e32 v119, 1, v128
	v_cndmask_b32_e32 v129, v128, v129, vcc
	v_fma_f32 v118, -v119, v128, v127
	v_cmp_lt_f32_e32 vcc, 0, v118
	s_nop 1
	v_cndmask_b32_e32 v128, v129, v119, vcc
	s_mov_b64 exec, 1
	global_store_dword v132, v125, s[98:99]
	v_add_u32_e32 v132, 0x2000, v132
	global_store_dword v132, v128, s[98:99]
	v_add_u32_e32 v132, 0x2000, v132
	s_mov_b64 exec, -1
	global_load_dwordx4 v[0:3], v130, s[100:101] nt
	global_load_dwordx4 v[4:7], v130, s[100:101] offset:1024 nt
	global_load_dwordx4 v[8:11], v130, s[100:101] offset:2048 nt
	global_load_dwordx4 v[12:15], v130, s[100:101] offset:3072 nt
	v_add_u32_e32 v130, 0x800000, v130
	global_load_dwordx4 v[16:19], v130, s[100:101] nt
	global_load_dwordx4 v[20:23], v130, s[100:101] offset:1024 nt
	global_load_dwordx4 v[24:27], v130, s[100:101] offset:2048 nt
	global_load_dwordx4 v[28:31], v130, s[100:101] offset:3072 nt
	v_add_u32_e32 v130, 0x800000, v130
	s_waitcnt vmcnt(22)
	v_pk_mul_f32 v[64:65], v[32:33], v[32:33]
	v_pk_fma_f32 v[64:65], v[34:35], v[34:35], v[64:65]
	v_pk_fma_f32 v[64:65], v[36:37], v[36:37], v[64:65]
	v_pk_fma_f32 v[64:65], v[38:39], v[38:39], v[64:65]
	v_pk_fma_f32 v[64:65], v[40:41], v[40:41], v[64:65]
	v_pk_fma_f32 v[64:65], v[42:43], v[42:43], v[64:65]
	v_pk_fma_f32 v[64:65], v[44:45], v[44:45], v[64:65]
	v_pk_fma_f32 v[64:65], v[46:47], v[46:47], v[64:65]
	s_nop 0
	v_add_f32_e32 v64, v64, v65
	s_waitcnt vmcnt(18)
	v_pk_mul_f32 v[66:67], v[48:49], v[48:49]
	v_pk_fma_f32 v[66:67], v[50:51], v[50:51], v[66:67]
	v_pk_fma_f32 v[66:67], v[52:53], v[52:53], v[66:67]
	v_pk_fma_f32 v[66:67], v[54:55], v[54:55], v[66:67]
	v_pk_fma_f32 v[66:67], v[56:57], v[56:57], v[66:67]
	v_pk_fma_f32 v[66:67], v[58:59], v[58:59], v[66:67]
	v_pk_fma_f32 v[66:67], v[60:61], v[60:61], v[66:67]
	v_pk_fma_f32 v[66:67], v[62:63], v[62:63], v[66:67]
	s_nop 0
	v_add_f32_e32 v66, v66, v67
	s_nop 1
	v_add_f32_dpp v64, v64, v64 quad_perm:[1,0,3,2] row_mask:0xf bank_mask:0xf
	v_add_f32_dpp v66, v66, v66 quad_perm:[1,0,3,2] row_mask:0xf bank_mask:0xf
	s_nop 0
	v_add_f32_dpp v64, v64, v64 quad_perm:[2,3,0,1] row_mask:0xf bank_mask:0xf
	v_add_f32_dpp v66, v66, v66 quad_perm:[2,3,0,1] row_mask:0xf bank_mask:0xf
	s_nop 0
	v_add_f32_dpp v64, v64, v64 row_half_mirror row_mask:0xf bank_mask:0xf
	v_add_f32_dpp v66, v66, v66 row_half_mirror row_mask:0xf bank_mask:0xf
	s_nop 0
	v_add_f32_dpp v64, v64, v64 row_mirror row_mask:0xf bank_mask:0xf
	v_add_f32_dpp v66, v66, v66 row_mirror row_mask:0xf bank_mask:0xf
	s_nop 0
	ds_bpermute_b32 v68, v71, v64
	ds_bpermute_b32 v69, v71, v66
	s_waitcnt lgkmcnt(0)
	v_add_f32_e32 v64, v64, v68
	v_add_f32_e32 v66, v66, v69
	ds_bpermute_b32 v68, v72, v64
	ds_bpermute_b32 v69, v72, v66
	s_waitcnt lgkmcnt(0)
; __device__ __forceinline__ const float* xrow_ptr(const Ctx& C, int row) { return row < MPROMPT ? C.in(0) + (size_t)row * DM : C.in(1) + (size_t)(row - MPROMPT) * DM; }
; __device__ __forceinline__ void st4_bf16(bf16* p, v4f o) { v2u w; w.x = cvt_pk_nv(o.x, o.y); w.y = cvt_pk_nv(o.z, o.w); *(v2u*)p = w; }
; __device__ __forceinline__ float ssq4(v4f v) { return (v.x * v.x + v.y * v.y) + (v.z * v.z + v.w * v.w); }
; template <int R>
; __device__ __forceinline__ void rows_x0(const Ctx& C, int m0, int stride, int mx, int lane) {
;     v4f v[R][4]; float ss[R]; int mr[R]; bool ok[R];
; #pragma unroll
;     for (int r = 0; r < R; ++r) { mr[r] = (r == 4) ? mx : m0 + r * stride; ok[r] = (r == 4) ? (mx < M) : (mr[r] < MPROMPT); const float* x = xrow_ptr(C, ok[r] ? mr[r] : 0);
; #pragma unroll
;         for (int j = 0; j < 4; ++j) v[r][j] = __builtin_nontemporal_load((const v4f*)(x + 4 * lane + 256 * j)); }
;     bf16* XN = C.XN();
; #pragma unroll
;     for (int r = 0; r < R; ++r) { float s = 0.f;
; #pragma unroll
;         for (int j = 0; j < 4; ++j) s += ssq4(v[r][j]);
;         ss[r] = s; }
;     float* rs = C.RS();
; #pragma unroll
;     for (int r = 0; r < R; ++r) ss[r] = wave_sum(ss[r]) * (1.f / DM) + EPS;
; #pragma unroll
;     for (int r = 0; r < R; ++r) { const float rstd = rsqrtf(ss[r]);
; #pragma unroll
;         for (int j = 0; j < 4; ++j) if (ok[r]) st4_bf16(XN + (size_t)mr[r] * DM + 4 * lane + 256 * j, v[r][j] * rstd);
;         if (lane == 0 && ok[r]) rs[mr[r]] = sqrtf(ss[r]); }
	v_add_f32_e32 v64, v64, v68
	v_add_f32_e32 v66, v66, v69
	v_fmamk_f32 v124, v64, 0x3a800000, v70
	v_fmamk_f32 v127, v66, 0x3a800000, v70
	s_nop 0
	v_rsq_f32_e32 v64, v124
	v_rsq_f32_e32 v66, v127
	v_sqrt_f32_e32 v125, v124
	v_sqrt_f32_e32 v128, v127
	s_nop 1
	v_pk_mul_f32 v[116:117], v[32:33], v[64:65] op_sel_hi:[1,0]
	v_cvt_pk_bf16_f32 v100, v116, v117
	v_pk_mul_f32 v[118:119], v[34:35], v[64:65] op_sel_hi:[1,0]
	v_cvt_pk_bf16_f32 v101, v118, v119
	v_pk_mul_f32 v[120:121], v[36:37], v[64:65] op_sel_hi:[1,0]
	v_cvt_pk_bf16_f32 v102, v120, v121
	v_pk_mul_f32 v[122:123], v[38:39], v[64:65] op_sel_hi:[1,0]
	v_cvt_pk_bf16_f32 v103, v122, v123
	v_pk_mul_f32 v[116:117], v[40:41], v[64:65] op_sel_hi:[1,0]
	v_cvt_pk_bf16_f32 v104, v116, v117
	v_pk_mul_f32 v[118:119], v[42:43], v[64:65] op_sel_hi:[1,0]
	v_cvt_pk_bf16_f32 v105, v118, v119
	v_pk_mul_f32 v[120:121], v[44:45], v[64:65] op_sel_hi:[1,0]
	v_cvt_pk_bf16_f32 v106, v120, v121
	v_pk_mul_f32 v[122:123], v[46:47], v[64:65] op_sel_hi:[1,0]
	v_cvt_pk_bf16_f32 v107, v122, v123
	global_store_dwordx2 v131, v[100:101], s[98:99]
	global_store_dwordx2 v131, v[102:103], s[98:99] offset:512
	global_store_dwordx2 v131, v[104:105], s[98:99] offset:1024
	global_store_dwordx2 v131, v[106:107], s[98:99] offset:1536
	v_add_u32_e32 v131, 0x400000, v131
	v_pk_mul_f32 v[116:117], v[48:49], v[66:67] op_sel_hi:[1,0]
	v_cvt_pk_bf16_f32 v108, v116, v117
	v_pk_mul_f32 v[118:119], v[50:51], v[66:67] op_sel_hi:[1,0]
	v_cvt_pk_bf16_f32 v109, v118, v119
	v_pk_mul_f32 v[120:121], v[52:53], v[66:67] op_sel_hi:[1,0]
	v_cvt_pk_bf16_f32 v110, v120, v121
	v_pk_mul_f32 v[122:123], v[54:55], v[66:67] op_sel_hi:[1,0]
	v_cvt_pk_bf16_f32 v111, v122, v123
	v_pk_mul_f32 v[116:117], v[56:57], v[66:67] op_sel_hi:[1,0]
	v_cvt_pk_bf16_f32 v112, v116, v117
	v_pk_mul_f32 v[118:119], v[58:59], v[66:67] op_sel_hi:[1,0]
	v_cvt_pk_bf16_f32 v113, v118, v119
	v_pk_mul_f32 v[120:121], v[60:61], v[66:67] op_sel_hi:[1,0]
	v_cvt_pk_bf16_f32 v114, v120, v121
	v_pk_mul_f32 v[122:123], v[62:63], v[66:67] op_sel_hi:[1,0]
	v_cvt_pk_bf16_f32 v115, v122, v123
	global_store_dwordx2 v131, v[108:109], s[98:99]
	global_store_dwordx2 v131, v[110:111], s[98:99] offset:512
	global_store_dwordx2 v131, v[112:113], s[98:99] offset:1024
	global_store_dwordx2 v131, v[114:115], s[98:99] offset:1536
	v_add_u32_e32 v131, 0x400000, v131
	v_add_u32_e32 v126, -1, v125
	v_fma_f32 v116, -v126, v125, v124
	v_cmp_ge_f32_e32 vcc, 0, v116
	v_add_u32_e32 v117, 1, v125
	v_cndmask_b32_e32 v126, v125, v126, vcc
	v_fma_f32 v116, -v117, v125, v124
	v_cmp_lt_f32_e32 vcc, 0, v116
	s_nop 1
	v_cndmask_b32_e32 v125, v126, v117, vcc
	v_add_u32_e32 v129, -1, v128
	v_fma_f32 v118, -v129, v128, v127
	v_cmp_ge_f32_e32 vcc, 0, v118
	v_add_u32_e32 v119, 1, v128
	v_cndmask_b32_e32 v129, v128, v129, vcc
	v_fma_f32 v118, -v119, v128, v127
	v_cmp_lt_f32_e32 vcc, 0, v118
	s_nop 1
	v_cndmask_b32_e32 v128, v129, v119, vcc
	s_mov_b64 exec, 1
	global_store_dword v132, v125, s[98:99]
	v_add_u32_e32 v132, 0x2000, v132
	global_store_dword v132, v128, s[98:99]
	v_add_u32_e32 v132, 0x2000, v132
	s_mov_b64 exec, -1
	global_load_dwordx4 v[32:35], v130, s[100:101] nt
	global_load_dwordx4 v[36:39], v130, s[100:101] offset:1024 nt
	global_load_dwordx4 v[40:43], v130, s[100:101] offset:2048 nt
	global_load_dwordx4 v[44:47], v130, s[100:101] offset:3072 nt
	v_add_u32_e32 v130, 0x800000, v130
	global_load_dwordx4 v[48:51], v130, s[100:101] nt
	global_load_dwordx4 v[52:55], v130, s[100:101] offset:1024 nt
	global_load_dwordx4 v[56:59], v130, s[100:101] offset:2048 nt
	global_load_dwordx4 v[60:63], v130, s[100:101] offset:3072 nt
	v_add_u32_e32 v130, 0x800000, v130
	s_waitcnt vmcnt(22)
	v_pk_mul_f32 v[64:65], v[0:1], v[0:1]
	v_pk_fma_f32 v[64:65], v[2:3], v[2:3], v[64:65]
	v_pk_fma_f32 v[64:65], v[4:5], v[4:5], v[64:65]
	v_pk_fma_f32 v[64:65], v[6:7], v[6:7], v[64:65]
	v_pk_fma_f32 v[64:65], v[8:9], v[8:9], v[64:65]
	v_pk_fma_f32 v[64:65], v[10:11], v[10:11], v[64:65]
	v_pk_fma_f32 v[64:65], v[12:13], v[12:13], v[64:65]
	v_pk_fma_f32 v[64:65], v[14:15], v[14:15], v[64:65]
	s_nop 0
	v_add_f32_e32 v64, v64, v65
	s_waitcnt vmcnt(18)
	v_pk_mul_f32 v[66:67], v[16:17], v[16:17]
	v_pk_fma_f32 v[66:67], v[18:19], v[18:19], v[66:67]
	v_pk_fma_f32 v[66:67], v[20:21], v[20:21], v[66:67]
	v_pk_fma_f32 v[66:67], v[22:23], v[22:23], v[66:67]
	v_pk_fma_f32 v[66:67], v[24:25], v[24:25], v[66:67]
	v_pk_fma_f32 v[66:67], v[26:27], v[26:27], v[66:67]
	v_pk_fma_f32 v[66:67], v[28:29], v[28:29], v[66:67]
	v_pk_fma_f32 v[66:67], v[30:31], v[30:31], v[66:67]
	s_nop 0
	v_add_f32_e32 v66, v66, v67
	s_nop 1
	v_add_f32_dpp v64, v64, v64 quad_perm:[1,0,3,2] row_mask:0xf bank_mask:0xf
	v_add_f32_dpp v66, v66, v66 quad_perm:[1,0,3,2] row_mask:0xf bank_mask:0xf
	s_nop 0
	v_add_f32_dpp v64, v64, v64 quad_perm:[2,3,0,1] row_mask:0xf bank_mask:0xf
	v_add_f32_dpp v66, v66, v66 quad_perm:[2,3,0,1] row_mask:0xf bank_mask:0xf
	s_nop 0
	v_add_f32_dpp v64, v64, v64 row_half_mirror row_mask:0xf bank_mask:0xf
	v_add_f32_dpp v66, v66, v66 row_half_mirror row_mask:0xf bank_mask:0xf
	s_nop 0
	v_add_f32_dpp v64, v64, v64 row_mirror row_mask:0xf bank_mask:0xf
	v_add_f32_dpp v66, v66, v66 row_mirror row_mask:0xf bank_mask:0xf
	s_nop 0
	ds_bpermute_b32 v68, v71, v64
	ds_bpermute_b32 v69, v71, v66
	s_waitcnt lgkmcnt(0)
	v_add_f32_e32 v64, v64, v68
	v_add_f32_e32 v66, v66, v69
	ds_bpermute_b32 v68, v72, v64
	ds_bpermute_b32 v69, v72, v66
	s_waitcnt lgkmcnt(0)
; __device__ __forceinline__ const float* xrow_ptr(const Ctx& C, int row) { return row < MPROMPT ? C.in(0) + (size_t)row * DM : C.in(1) + (size_t)(row - MPROMPT) * DM; }
; __device__ __forceinline__ void st4_bf16(bf16* p, v4f o) { v2u w; w.x = cvt_pk_nv(o.x, o.y); w.y = cvt_pk_nv(o.z, o.w); *(v2u*)p = w; }
; __device__ __forceinline__ float ssq4(v4f v) { return (v.x * v.x + v.y * v.y) + (v.z * v.z + v.w * v.w); }
; template <int R>
; __device__ __forceinline__ void rows_x0(const Ctx& C, int m0, int stride, int mx, int lane) {
;     v4f v[R][4]; float ss[R]; int mr[R]; bool ok[R];
; #pragma unroll
;     for (int r = 0; r < R; ++r) { mr[r] = (r == 4) ? mx : m0 + r * stride; ok[r] = (r == 4) ? (mx < M) : (mr[r] < MPROMPT); const float* x = xrow_ptr(C, ok[r] ? mr[r] : 0);
; #pragma unroll
;         for (int j = 0; j < 4; ++j) v[r][j] = __builtin_nontemporal_load((const v4f*)(x + 4 * lane + 256 * j)); }
;     bf16* XN = C.XN();
; #pragma unroll
;     for (int r = 0; r < R; ++r) { float s = 0.f;
; #pragma unroll
;         for (int j = 0; j < 4; ++j) s += ssq4(v[r][j]);
;         ss[r] = s; }
;     float* rs = C.RS();
; #pragma unroll
;     for (int r = 0; r < R; ++r) ss[r] = wave_sum(ss[r]) * (1.f / DM) + EPS;
; #pragma unroll
;     for (int r = 0; r < R; ++r) { const float rstd = rsqrtf(ss[r]);
; #pragma unroll
;         for (int j = 0; j < 4; ++j) if (ok[r]) st4_bf16(XN + (size_t)mr[r] * DM + 4 * lane + 256 * j, v[r][j] * rstd);
;         if (lane == 0 && ok[r]) rs[mr[r]] = sqrtf(ss[r]); }
	v_add_f32_e32 v64, v64, v68
	v_add_f32_e32 v66, v66, v69
	v_fmamk_f32 v124, v64, 0x3a800000, v70
	v_fmamk_f32 v127, v66, 0x3a800000, v70
	s_nop 0
	v_rsq_f32_e32 v64, v124
	v_rsq_f32_e32 v66, v127
	v_sqrt_f32_e32 v125, v124
	v_sqrt_f32_e32 v128, v127
	s_nop 1
	v_pk_mul_f32 v[116:117], v[0:1], v[64:65] op_sel_hi:[1,0]
	v_cvt_pk_bf16_f32 v100, v116, v117
	v_pk_mul_f32 v[118:119], v[2:3], v[64:65] op_sel_hi:[1,0]
	v_cvt_pk_bf16_f32 v101, v118, v119
	v_pk_mul_f32 v[120:121], v[4:5], v[64:65] op_sel_hi:[1,0]
	v_cvt_pk_bf16_f32 v102, v120, v121
	v_pk_mul_f32 v[122:123], v[6:7], v[64:65] op_sel_hi:[1,0]
	v_cvt_pk_bf16_f32 v103, v122, v123
	v_pk_mul_f32 v[116:117], v[8:9], v[64:65] op_sel_hi:[1,0]
	v_cvt_pk_bf16_f32 v104, v116, v117
	v_pk_mul_f32 v[118:119], v[10:11], v[64:65] op_sel_hi:[1,0]
	v_cvt_pk_bf16_f32 v105, v118, v119
	v_pk_mul_f32 v[120:121], v[12:13], v[64:65] op_sel_hi:[1,0]
	v_cvt_pk_bf16_f32 v106, v120, v121
	v_pk_mul_f32 v[122:123], v[14:15], v[64:65] op_sel_hi:[1,0]
	v_cvt_pk_bf16_f32 v107, v122, v123
	global_store_dwordx2 v131, v[100:101], s[98:99]
	global_store_dwordx2 v131, v[102:103], s[98:99] offset:512
	global_store_dwordx2 v131, v[104:105], s[98:99] offset:1024
	global_store_dwordx2 v131, v[106:107], s[98:99] offset:1536
	v_add_u32_e32 v131, 0x400000, v131
	v_pk_mul_f32 v[116:117], v[16:17], v[66:67] op_sel_hi:[1,0]
	v_cvt_pk_bf16_f32 v108, v116, v117
	v_pk_mul_f32 v[118:119], v[18:19], v[66:67] op_sel_hi:[1,0]
	v_cvt_pk_bf16_f32 v109, v118, v119
	v_pk_mul_f32 v[120:121], v[20:21], v[66:67] op_sel_hi:[1,0]
	v_cvt_pk_bf16_f32 v110, v120, v121
	v_pk_mul_f32 v[122:123], v[22:23], v[66:67] op_sel_hi:[1,0]
	v_cvt_pk_bf16_f32 v111, v122, v123
	v_pk_mul_f32 v[116:117], v[24:25], v[66:67] op_sel_hi:[1,0]
	v_cvt_pk_bf16_f32 v112, v116, v117
	v_pk_mul_f32 v[118:119], v[26:27], v[66:67] op_sel_hi:[1,0]
	v_cvt_pk_bf16_f32 v113, v118, v119
	v_pk_mul_f32 v[120:121], v[28:29], v[66:67] op_sel_hi:[1,0]
	v_cvt_pk_bf16_f32 v114, v120, v121
	v_pk_mul_f32 v[122:123], v[30:31], v[66:67] op_sel_hi:[1,0]
	v_cvt_pk_bf16_f32 v115, v122, v123
	global_store_dwordx2 v131, v[108:109], s[98:99]
	global_store_dwordx2 v131, v[110:111], s[98:99] offset:512
	global_store_dwordx2 v131, v[112:113], s[98:99] offset:1024
	global_store_dwordx2 v131, v[114:115], s[98:99] offset:1536
	v_add_u32_e32 v131, 0x400000, v131
	v_add_u32_e32 v126, -1, v125
	v_fma_f32 v116, -v126, v125, v124
	v_cmp_ge_f32_e32 vcc, 0, v116
	v_add_u32_e32 v117, 1, v125
	v_cndmask_b32_e32 v126, v125, v126, vcc
	v_fma_f32 v116, -v117, v125, v124
	v_cmp_lt_f32_e32 vcc, 0, v116
	s_nop 1
	v_cndmask_b32_e32 v125, v126, v117, vcc
	v_add_u32_e32 v129, -1, v128
	v_fma_f32 v118, -v129, v128, v127
	v_cmp_ge_f32_e32 vcc, 0, v118
	v_add_u32_e32 v119, 1, v128
	v_cndmask_b32_e32 v129, v128, v129, vcc
	v_fma_f32 v118, -v119, v128, v127
	v_cmp_lt_f32_e32 vcc, 0, v118
	s_nop 1
	v_cndmask_b32_e32 v128, v129, v119, vcc
	s_mov_b64 exec, 1
	global_store_dword v132, v125, s[98:99]
	v_add_u32_e32 v132, 0x2000, v132
	global_store_dword v132, v128, s[98:99]
	v_add_u32_e32 v132, 0x2000, v132
	s_mov_b64 exec, -1
	global_load_dwordx4 v[0:3], v130, s[100:101] nt
	global_load_dwordx4 v[4:7], v130, s[100:101] offset:1024 nt
	global_load_dwordx4 v[8:11], v130, s[100:101] offset:2048 nt
	global_load_dwordx4 v[12:15], v130, s[100:101] offset:3072 nt
	v_add_u32_e32 v130, 0x800000, v130
	global_load_dwordx4 v[16:19], v130, s[100:101] nt
	global_load_dwordx4 v[20:23], v130, s[100:101] offset:1024 nt
	global_load_dwordx4 v[24:27], v130, s[100:101] offset:2048 nt
	global_load_dwordx4 v[28:31], v130, s[100:101] offset:3072 nt
	v_add_u32_e32 v130, 0x800000, v130
	s_waitcnt vmcnt(22)
	v_pk_mul_f32 v[64:65], v[32:33], v[32:33]
	v_pk_fma_f32 v[64:65], v[34:35], v[34:35], v[64:65]
	v_pk_fma_f32 v[64:65], v[36:37], v[36:37], v[64:65]
	v_pk_fma_f32 v[64:65], v[38:39], v[38:39], v[64:65]
	v_pk_fma_f32 v[64:65], v[40:41], v[40:41], v[64:65]
	v_pk_fma_f32 v[64:65], v[42:43], v[42:43], v[64:65]
	v_pk_fma_f32 v[64:65], v[44:45], v[44:45], v[64:65]
	v_pk_fma_f32 v[64:65], v[46:47], v[46:47], v[64:65]
	s_nop 0
	v_add_f32_e32 v64, v64, v65
	s_waitcnt vmcnt(18)
	v_pk_mul_f32 v[66:67], v[48:49], v[48:49]
	v_pk_fma_f32 v[66:67], v[50:51], v[50:51], v[66:67]
	v_pk_fma_f32 v[66:67], v[52:53], v[52:53], v[66:67]
	v_pk_fma_f32 v[66:67], v[54:55], v[54:55], v[66:67]
	v_pk_fma_f32 v[66:67], v[56:57], v[56:57], v[66:67]
	v_pk_fma_f32 v[66:67], v[58:59], v[58:59], v[66:67]
	v_pk_fma_f32 v[66:67], v[60:61], v[60:61], v[66:67]
	v_pk_fma_f32 v[66:67], v[62:63], v[62:63], v[66:67]
	s_nop 0
	v_add_f32_e32 v66, v66, v67
	s_nop 1
	v_add_f32_dpp v64, v64, v64 quad_perm:[1,0,3,2] row_mask:0xf bank_mask:0xf
	v_add_f32_dpp v66, v66, v66 quad_perm:[1,0,3,2] row_mask:0xf bank_mask:0xf
	s_nop 0
	v_add_f32_dpp v64, v64, v64 quad_perm:[2,3,0,1] row_mask:0xf bank_mask:0xf
	v_add_f32_dpp v66, v66, v66 quad_perm:[2,3,0,1] row_mask:0xf bank_mask:0xf
	s_nop 0
	v_add_f32_dpp v64, v64, v64 row_half_mirror row_mask:0xf bank_mask:0xf
	v_add_f32_dpp v66, v66, v66 row_half_mirror row_mask:0xf bank_mask:0xf
	s_nop 0
	v_add_f32_dpp v64, v64, v64 row_mirror row_mask:0xf bank_mask:0xf
	v_add_f32_dpp v66, v66, v66 row_mirror row_mask:0xf bank_mask:0xf
	s_nop 0
	ds_bpermute_b32 v68, v71, v64
	ds_bpermute_b32 v69, v71, v66
	s_waitcnt lgkmcnt(0)
	v_add_f32_e32 v64, v64, v68
	v_add_f32_e32 v66, v66, v69
	ds_bpermute_b32 v68, v72, v64
	ds_bpermute_b32 v69, v72, v66
	s_waitcnt lgkmcnt(0)
; __device__ __forceinline__ const float* xrow_ptr(const Ctx& C, int row) { return row < MPROMPT ? C.in(0) + (size_t)row * DM : C.in(1) + (size_t)(row - MPROMPT) * DM; }
; __device__ __forceinline__ void st4_bf16(bf16* p, v4f o) { v2u w; w.x = cvt_pk_nv(o.x, o.y); w.y = cvt_pk_nv(o.z, o.w); *(v2u*)p = w; }
; __device__ __forceinline__ float ssq4(v4f v) { return (v.x * v.x + v.y * v.y) + (v.z * v.z + v.w * v.w); }
; template <int R>
; __device__ __forceinline__ void rows_x0(const Ctx& C, int m0, int stride, int mx, int lane) {
;     v4f v[R][4]; float ss[R]; int mr[R]; bool ok[R];
; #pragma unroll
;     for (int r = 0; r < R; ++r) { mr[r] = (r == 4) ? mx : m0 + r * stride; ok[r] = (r == 4) ? (mx < M) : (mr[r] < MPROMPT); const float* x = xrow_ptr(C, ok[r] ? mr[r] : 0);
; #pragma unroll
;         for (int j = 0; j < 4; ++j) v[r][j] = __builtin_nontemporal_load((const v4f*)(x + 4 * lane + 256 * j)); }
;     bf16* XN = C.XN();
; #pragma unroll
;     for (int r = 0; r < R; ++r) { float s = 0.f;
; #pragma unroll
;         for (int j = 0; j < 4; ++j) s += ssq4(v[r][j]);
;         ss[r] = s; }
;     float* rs = C.RS();
; #pragma unroll
;     for (int r = 0; r < R; ++r) ss[r] = wave_sum(ss[r]) * (1.f / DM) + EPS;
; #pragma unroll
;     for (int r = 0; r < R; ++r) { const float rstd = rsqrtf(ss[r]);
; #pragma unroll
;         for (int j = 0; j < 4; ++j) if (ok[r]) st4_bf16(XN + (size_t)mr[r] * DM + 4 * lane + 256 * j, v[r][j] * rstd);
;         if (lane == 0 && ok[r]) rs[mr[r]] = sqrtf(ss[r]); }
	v_add_f32_e32 v64, v64, v68
	v_add_f32_e32 v66, v66, v69
	v_fmamk_f32 v124, v64, 0x3a800000, v70
	v_fmamk_f32 v127, v66, 0x3a800000, v70
	s_nop 0
	v_rsq_f32_e32 v64, v124
	v_rsq_f32_e32 v66, v127
	v_sqrt_f32_e32 v125, v124
	v_sqrt_f32_e32 v128, v127
	s_nop 1
	v_pk_mul_f32 v[116:117], v[32:33], v[64:65] op_sel_hi:[1,0]
	v_cvt_pk_bf16_f32 v100, v116, v117
	v_pk_mul_f32 v[118:119], v[34:35], v[64:65] op_sel_hi:[1,0]
	v_cvt_pk_bf16_f32 v101, v118, v119
	v_pk_mul_f32 v[120:121], v[36:37], v[64:65] op_sel_hi:[1,0]
	v_cvt_pk_bf16_f32 v102, v120, v121
	v_pk_mul_f32 v[122:123], v[38:39], v[64:65] op_sel_hi:[1,0]
	v_cvt_pk_bf16_f32 v103, v122, v123
	v_pk_mul_f32 v[116:117], v[40:41], v[64:65] op_sel_hi:[1,0]
	v_cvt_pk_bf16_f32 v104, v116, v117
	v_pk_mul_f32 v[118:119], v[42:43], v[64:65] op_sel_hi:[1,0]
	v_cvt_pk_bf16_f32 v105, v118, v119
	v_pk_mul_f32 v[120:121], v[44:45], v[64:65] op_sel_hi:[1,0]
	v_cvt_pk_bf16_f32 v106, v120, v121
	v_pk_mul_f32 v[122:123], v[46:47], v[64:65] op_sel_hi:[1,0]
	v_cvt_pk_bf16_f32 v107, v122, v123
	global_store_dwordx2 v131, v[100:101], s[98:99]
	global_store_dwordx2 v131, v[102:103], s[98:99] offset:512
	global_store_dwordx2 v131, v[104:105], s[98:99] offset:1024
	global_store_dwordx2 v131, v[106:107], s[98:99] offset:1536
	v_add_u32_e32 v131, 0x400000, v131
	v_pk_mul_f32 v[116:117], v[48:49], v[66:67] op_sel_hi:[1,0]
	v_cvt_pk_bf16_f32 v108, v116, v117
	v_pk_mul_f32 v[118:119], v[50:51], v[66:67] op_sel_hi:[1,0]
	v_cvt_pk_bf16_f32 v109, v118, v119
	v_pk_mul_f32 v[120:121], v[52:53], v[66:67] op_sel_hi:[1,0]
	v_cvt_pk_bf16_f32 v110, v120, v121
	v_pk_mul_f32 v[122:123], v[54:55], v[66:67] op_sel_hi:[1,0]
	v_cvt_pk_bf16_f32 v111, v122, v123
	v_pk_mul_f32 v[116:117], v[56:57], v[66:67] op_sel_hi:[1,0]
	v_cvt_pk_bf16_f32 v112, v116, v117
	v_pk_mul_f32 v[118:119], v[58:59], v[66:67] op_sel_hi:[1,0]
	v_cvt_pk_bf16_f32 v113, v118, v119
	v_pk_mul_f32 v[120:121], v[60:61], v[66:67] op_sel_hi:[1,0]
	v_cvt_pk_bf16_f32 v114, v120, v121
	v_pk_mul_f32 v[122:123], v[62:63], v[66:67] op_sel_hi:[1,0]
	v_cvt_pk_bf16_f32 v115, v122, v123
	global_store_dwordx2 v131, v[108:109], s[98:99]
	global_store_dwordx2 v131, v[110:111], s[98:99] offset:512
	global_store_dwordx2 v131, v[112:113], s[98:99] offset:1024
	global_store_dwordx2 v131, v[114:115], s[98:99] offset:1536
	v_add_u32_e32 v131, 0x400000, v131
	v_add_u32_e32 v126, -1, v125
	v_fma_f32 v116, -v126, v125, v124
	v_cmp_ge_f32_e32 vcc, 0, v116
	v_add_u32_e32 v117, 1, v125
	v_cndmask_b32_e32 v126, v125, v126, vcc
	v_fma_f32 v116, -v117, v125, v124
	v_cmp_lt_f32_e32 vcc, 0, v116
	s_nop 1
	v_cndmask_b32_e32 v125, v126, v117, vcc
	v_add_u32_e32 v129, -1, v128
	v_fma_f32 v118, -v129, v128, v127
	v_cmp_ge_f32_e32 vcc, 0, v118
	v_add_u32_e32 v119, 1, v128
	v_cndmask_b32_e32 v129, v128, v129, vcc
	v_fma_f32 v118, -v119, v128, v127
	v_cmp_lt_f32_e32 vcc, 0, v118
	s_nop 1
	v_cndmask_b32_e32 v128, v129, v119, vcc
	s_mov_b64 exec, 1
	global_store_dword v132, v125, s[98:99]
	v_add_u32_e32 v132, 0x2000, v132
	global_store_dword v132, v128, s[98:99]
	v_add_u32_e32 v132, 0x2000, v132
	s_mov_b64 exec, -1
	global_load_dwordx4 v[32:35], v130, s[100:101] nt
	global_load_dwordx4 v[36:39], v130, s[100:101] offset:1024 nt
	global_load_dwordx4 v[40:43], v130, s[100:101] offset:2048 nt
	global_load_dwordx4 v[44:47], v130, s[100:101] offset:3072 nt
	v_add_u32_e32 v130, 0x800000, v130
	global_load_dwordx4 v[48:51], v130, s[100:101] nt
	global_load_dwordx4 v[52:55], v130, s[100:101] offset:1024 nt
	global_load_dwordx4 v[56:59], v130, s[100:101] offset:2048 nt
	global_load_dwordx4 v[60:63], v130, s[100:101] offset:3072 nt
	v_add_u32_e32 v130, 0x800000, v130
	s_waitcnt vmcnt(22)
	v_pk_mul_f32 v[64:65], v[0:1], v[0:1]
	v_pk_fma_f32 v[64:65], v[2:3], v[2:3], v[64:65]
	v_pk_fma_f32 v[64:65], v[4:5], v[4:5], v[64:65]
	v_pk_fma_f32 v[64:65], v[6:7], v[6:7], v[64:65]
	v_pk_fma_f32 v[64:65], v[8:9], v[8:9], v[64:65]
	v_pk_fma_f32 v[64:65], v[10:11], v[10:11], v[64:65]
	v_pk_fma_f32 v[64:65], v[12:13], v[12:13], v[64:65]
	v_pk_fma_f32 v[64:65], v[14:15], v[14:15], v[64:65]
	s_nop 0
	v_add_f32_e32 v64, v64, v65
	s_waitcnt vmcnt(18)
	v_pk_mul_f32 v[66:67], v[16:17], v[16:17]
	v_pk_fma_f32 v[66:67], v[18:19], v[18:19], v[66:67]
	v_pk_fma_f32 v[66:67], v[20:21], v[20:21], v[66:67]
	v_pk_fma_f32 v[66:67], v[22:23], v[22:23], v[66:67]
	v_pk_fma_f32 v[66:67], v[24:25], v[24:25], v[66:67]
	v_pk_fma_f32 v[66:67], v[26:27], v[26:27], v[66:67]
	v_pk_fma_f32 v[66:67], v[28:29], v[28:29], v[66:67]
	v_pk_fma_f32 v[66:67], v[30:31], v[30:31], v[66:67]
	s_nop 0
	v_add_f32_e32 v66, v66, v67
	s_nop 1
	v_add_f32_dpp v64, v64, v64 quad_perm:[1,0,3,2] row_mask:0xf bank_mask:0xf
	v_add_f32_dpp v66, v66, v66 quad_perm:[1,0,3,2] row_mask:0xf bank_mask:0xf
	s_nop 0
	v_add_f32_dpp v64, v64, v64 quad_perm:[2,3,0,1] row_mask:0xf bank_mask:0xf
	v_add_f32_dpp v66, v66, v66 quad_perm:[2,3,0,1] row_mask:0xf bank_mask:0xf
	s_nop 0
	v_add_f32_dpp v64, v64, v64 row_half_mirror row_mask:0xf bank_mask:0xf
	v_add_f32_dpp v66, v66, v66 row_half_mirror row_mask:0xf bank_mask:0xf
	s_nop 0
	v_add_f32_dpp v64, v64, v64 row_mirror row_mask:0xf bank_mask:0xf
	v_add_f32_dpp v66, v66, v66 row_mirror row_mask:0xf bank_mask:0xf
	s_nop 0
	ds_bpermute_b32 v68, v71, v64
	ds_bpermute_b32 v69, v71, v66
	s_waitcnt lgkmcnt(0)
	v_add_f32_e32 v64, v64, v68
	v_add_f32_e32 v66, v66, v69
	ds_bpermute_b32 v68, v72, v64
	ds_bpermute_b32 v69, v72, v66
	s_waitcnt lgkmcnt(0)
; __device__ __forceinline__ void st4_bf16(bf16* p, v4f o) { v2u w; w.x = cvt_pk_nv(o.x, o.y); w.y = cvt_pk_nv(o.z, o.w); *(v2u*)p = w; }
; __device__ __forceinline__ float ssq4(v4f v) { return (v.x * v.x + v.y * v.y) + (v.z * v.z + v.w * v.w); }
; template <int R>
; __device__ __forceinline__ void rows_x0(const Ctx& C, int m0, int stride, int mx, int lane) {
;     ...
;     for (int r = 0; r < R; ++r) { float s = 0.f;
; #pragma unroll
;         for (int j = 0; j < 4; ++j) s += ssq4(v[r][j]);
;         ss[r] = s; }
;     float* rs = C.RS();
; #pragma unroll
;     for (int r = 0; r < R; ++r) ss[r] = wave_sum(ss[r]) * (1.f / DM) + EPS;
; #pragma unroll
;     for (int r = 0; r < R; ++r) { const float rstd = rsqrtf(ss[r]);
; #pragma unroll
;         for (int j = 0; j < 4; ++j) if (ok[r]) st4_bf16(XN + (size_t)mr[r] * DM + 4 * lane + 256 * j, v[r][j] * rstd);
;         if (lane == 0 && ok[r]) rs[mr[r]] = sqrtf(ss[r]); }
	v_add_f32_e32 v64, v64, v68
	v_add_f32_e32 v66, v66, v69
	v_fmamk_f32 v124, v64, 0x3a800000, v70
	v_fmamk_f32 v127, v66, 0x3a800000, v70
	s_nop 0
	v_rsq_f32_e32 v64, v124
	v_rsq_f32_e32 v66, v127
	v_sqrt_f32_e32 v125, v124
	v_sqrt_f32_e32 v128, v127
	s_nop 1
	v_pk_mul_f32 v[116:117], v[0:1], v[64:65] op_sel_hi:[1,0]
	v_cvt_pk_bf16_f32 v100, v116, v117
	v_pk_mul_f32 v[118:119], v[2:3], v[64:65] op_sel_hi:[1,0]
	v_cvt_pk_bf16_f32 v101, v118, v119
	v_pk_mul_f32 v[120:121], v[4:5], v[64:65] op_sel_hi:[1,0]
	v_cvt_pk_bf16_f32 v102, v120, v121
	v_pk_mul_f32 v[122:123], v[6:7], v[64:65] op_sel_hi:[1,0]
	v_cvt_pk_bf16_f32 v103, v122, v123
	v_pk_mul_f32 v[116:117], v[8:9], v[64:65] op_sel_hi:[1,0]
	v_cvt_pk_bf16_f32 v104, v116, v117
	v_pk_mul_f32 v[118:119], v[10:11], v[64:65] op_sel_hi:[1,0]
	v_cvt_pk_bf16_f32 v105, v118, v119
	v_pk_mul_f32 v[120:121], v[12:13], v[64:65] op_sel_hi:[1,0]
	v_cvt_pk_bf16_f32 v106, v120, v121
	v_pk_mul_f32 v[122:123], v[14:15], v[64:65] op_sel_hi:[1,0]
	v_cvt_pk_bf16_f32 v107, v122, v123
	global_store_dwordx2 v131, v[100:101], s[98:99]
	global_store_dwordx2 v131, v[102:103], s[98:99] offset:512
	global_store_dwordx2 v131, v[104:105], s[98:99] offset:1024
	global_store_dwordx2 v131, v[106:107], s[98:99] offset:1536
	v_add_u32_e32 v131, 0x400000, v131
	v_pk_mul_f32 v[116:117], v[16:17], v[66:67] op_sel_hi:[1,0]
	v_cvt_pk_bf16_f32 v108, v116, v117
	v_pk_mul_f32 v[118:119], v[18:19], v[66:67] op_sel_hi:[1,0]
	v_cvt_pk_bf16_f32 v109, v118, v119
	v_pk_mul_f32 v[120:121], v[20:21], v[66:67] op_sel_hi:[1,0]
	v_cvt_pk_bf16_f32 v110, v120, v121
	v_pk_mul_f32 v[122:123], v[22:23], v[66:67] op_sel_hi:[1,0]
	v_cvt_pk_bf16_f32 v111, v122, v123
	v_pk_mul_f32 v[116:117], v[24:25], v[66:67] op_sel_hi:[1,0]
	v_cvt_pk_bf16_f32 v112, v116, v117
	v_pk_mul_f32 v[118:119], v[26:27], v[66:67] op_sel_hi:[1,0]
	v_cvt_pk_bf16_f32 v113, v118, v119
	v_pk_mul_f32 v[120:121], v[28:29], v[66:67] op_sel_hi:[1,0]
	v_cvt_pk_bf16_f32 v114, v120, v121
	v_pk_mul_f32 v[122:123], v[30:31], v[66:67] op_sel_hi:[1,0]
	v_cvt_pk_bf16_f32 v115, v122, v123
	global_store_dwordx2 v131, v[108:109], s[98:99]
	global_store_dwordx2 v131, v[110:111], s[98:99] offset:512
	global_store_dwordx2 v131, v[112:113], s[98:99] offset:1024
	global_store_dwordx2 v131, v[114:115], s[98:99] offset:1536
	v_add_u32_e32 v131, 0x400000, v131
	v_add_u32_e32 v126, -1, v125
	v_fma_f32 v116, -v126, v125, v124
	v_cmp_ge_f32_e32 vcc, 0, v116
	v_add_u32_e32 v117, 1, v125
	v_cndmask_b32_e32 v126, v125, v126, vcc
	v_fma_f32 v116, -v117, v125, v124
	v_cmp_lt_f32_e32 vcc, 0, v116
	s_nop 1
	v_cndmask_b32_e32 v125, v126, v117, vcc
	v_add_u32_e32 v129, -1, v128
	v_fma_f32 v118, -v129, v128, v127
	v_cmp_ge_f32_e32 vcc, 0, v118
	v_add_u32_e32 v119, 1, v128
	v_cndmask_b32_e32 v129, v128, v129, vcc
	v_fma_f32 v118, -v119, v128, v127
	v_cmp_lt_f32_e32 vcc, 0, v118
	s_nop 1
	v_cndmask_b32_e32 v128, v129, v119, vcc
	s_mov_b64 exec, 1
	global_store_dword v132, v125, s[98:99]
	v_add_u32_e32 v132, 0x2000, v132
	global_store_dword v132, v128, s[98:99]
	v_add_u32_e32 v132, 0x2000, v132
	s_mov_b64 exec, -1
	s_waitcnt vmcnt(14)
	v_pk_mul_f32 v[64:65], v[32:33], v[32:33]
	v_pk_fma_f32 v[64:65], v[34:35], v[34:35], v[64:65]
	v_pk_fma_f32 v[64:65], v[36:37], v[36:37], v[64:65]
	v_pk_fma_f32 v[64:65], v[38:39], v[38:39], v[64:65]
	v_pk_fma_f32 v[64:65], v[40:41], v[40:41], v[64:65]
	v_pk_fma_f32 v[64:65], v[42:43], v[42:43], v[64:65]
	v_pk_fma_f32 v[64:65], v[44:45], v[44:45], v[64:65]
	v_pk_fma_f32 v[64:65], v[46:47], v[46:47], v[64:65]
	s_nop 0
	v_add_f32_e32 v64, v64, v65
	s_waitcnt vmcnt(10)
; __device__ __forceinline__ void st4_bf16(bf16* p, v4f o) { v2u w; w.x = cvt_pk_nv(o.x, o.y); w.y = cvt_pk_nv(o.z, o.w); *(v2u*)p = w; }
; template <int R>
; __device__ __forceinline__ void rows_x0(const Ctx& C, int m0, int stride, int mx, int lane) {
;     ...
;     for (int r = 0; r < R; ++r) ss[r] = wave_sum(ss[r]) * (1.f / DM) + EPS;
; #pragma unroll
;     for (int r = 0; r < R; ++r) { const float rstd = rsqrtf(ss[r]);
; #pragma unroll
;         for (int j = 0; j < 4; ++j) if (ok[r]) st4_bf16(XN + (size_t)mr[r] * DM + 4 * lane + 256 * j, v[r][j] * rstd);
;         if (lane == 0 && ok[r]) rs[mr[r]] = sqrtf(ss[r]); }
	v_pk_mul_f32 v[66:67], v[48:49], v[48:49]
	v_pk_fma_f32 v[66:67], v[50:51], v[50:51], v[66:67]
	v_pk_fma_f32 v[66:67], v[52:53], v[52:53], v[66:67]
	v_pk_fma_f32 v[66:67], v[54:55], v[54:55], v[66:67]
	v_pk_fma_f32 v[66:67], v[56:57], v[56:57], v[66:67]
	v_pk_fma_f32 v[66:67], v[58:59], v[58:59], v[66:67]
	v_pk_fma_f32 v[66:67], v[60:61], v[60:61], v[66:67]
	v_pk_fma_f32 v[66:67], v[62:63], v[62:63], v[66:67]
	s_nop 0
	v_add_f32_e32 v66, v66, v67
	s_nop 1
	v_add_f32_dpp v64, v64, v64 quad_perm:[1,0,3,2] row_mask:0xf bank_mask:0xf
	v_add_f32_dpp v66, v66, v66 quad_perm:[1,0,3,2] row_mask:0xf bank_mask:0xf
	s_nop 0
	v_add_f32_dpp v64, v64, v64 quad_perm:[2,3,0,1] row_mask:0xf bank_mask:0xf
	v_add_f32_dpp v66, v66, v66 quad_perm:[2,3,0,1] row_mask:0xf bank_mask:0xf
	s_nop 0
	v_add_f32_dpp v64, v64, v64 row_half_mirror row_mask:0xf bank_mask:0xf
	v_add_f32_dpp v66, v66, v66 row_half_mirror row_mask:0xf bank_mask:0xf
	s_nop 0
	v_add_f32_dpp v64, v64, v64 row_mirror row_mask:0xf bank_mask:0xf
	v_add_f32_dpp v66, v66, v66 row_mirror row_mask:0xf bank_mask:0xf
	s_nop 0
	ds_bpermute_b32 v68, v71, v64
	ds_bpermute_b32 v69, v71, v66
	s_waitcnt lgkmcnt(0)
	v_add_f32_e32 v64, v64, v68
	v_add_f32_e32 v66, v66, v69
	ds_bpermute_b32 v68, v72, v64
	ds_bpermute_b32 v69, v72, v66
	s_waitcnt lgkmcnt(0)
	v_add_f32_e32 v64, v64, v68
	v_add_f32_e32 v66, v66, v69
	v_fmamk_f32 v124, v64, 0x3a800000, v70
	v_fmamk_f32 v127, v66, 0x3a800000, v70
	s_nop 0
	v_rsq_f32_e32 v64, v124
	v_rsq_f32_e32 v66, v127
	v_sqrt_f32_e32 v125, v124
	v_sqrt_f32_e32 v128, v127
	s_nop 1
	v_pk_mul_f32 v[116:117], v[32:33], v[64:65] op_sel_hi:[1,0]
	v_cvt_pk_bf16_f32 v100, v116, v117
	v_pk_mul_f32 v[118:119], v[34:35], v[64:65] op_sel_hi:[1,0]
	v_cvt_pk_bf16_f32 v101, v118, v119
	v_pk_mul_f32 v[120:121], v[36:37], v[64:65] op_sel_hi:[1,0]
	v_cvt_pk_bf16_f32 v102, v120, v121
	v_pk_mul_f32 v[122:123], v[38:39], v[64:65] op_sel_hi:[1,0]
	v_cvt_pk_bf16_f32 v103, v122, v123
	v_pk_mul_f32 v[116:117], v[40:41], v[64:65] op_sel_hi:[1,0]
	v_cvt_pk_bf16_f32 v104, v116, v117
	v_pk_mul_f32 v[118:119], v[42:43], v[64:65] op_sel_hi:[1,0]
	v_cvt_pk_bf16_f32 v105, v118, v119
	v_pk_mul_f32 v[120:121], v[44:45], v[64:65] op_sel_hi:[1,0]
	v_cvt_pk_bf16_f32 v106, v120, v121
	v_pk_mul_f32 v[122:123], v[46:47], v[64:65] op_sel_hi:[1,0]
	v_cvt_pk_bf16_f32 v107, v122, v123
	global_store_dwordx2 v131, v[100:101], s[98:99]
	global_store_dwordx2 v131, v[102:103], s[98:99] offset:512
	global_store_dwordx2 v131, v[104:105], s[98:99] offset:1024
	global_store_dwordx2 v131, v[106:107], s[98:99] offset:1536
	v_add_u32_e32 v131, 0x400000, v131
	v_pk_mul_f32 v[116:117], v[48:49], v[66:67] op_sel_hi:[1,0]
	v_cvt_pk_bf16_f32 v108, v116, v117
	v_pk_mul_f32 v[118:119], v[50:51], v[66:67] op_sel_hi:[1,0]
	v_cvt_pk_bf16_f32 v109, v118, v119
	v_pk_mul_f32 v[120:121], v[52:53], v[66:67] op_sel_hi:[1,0]
	v_cvt_pk_bf16_f32 v110, v120, v121
	v_pk_mul_f32 v[122:123], v[54:55], v[66:67] op_sel_hi:[1,0]
	v_cvt_pk_bf16_f32 v111, v122, v123
	v_pk_mul_f32 v[116:117], v[56:57], v[66:67] op_sel_hi:[1,0]
	v_cvt_pk_bf16_f32 v112, v116, v117
	v_pk_mul_f32 v[118:119], v[58:59], v[66:67] op_sel_hi:[1,0]
	v_cvt_pk_bf16_f32 v113, v118, v119
	v_pk_mul_f32 v[120:121], v[60:61], v[66:67] op_sel_hi:[1,0]
	v_cvt_pk_bf16_f32 v114, v120, v121
	v_pk_mul_f32 v[122:123], v[62:63], v[66:67] op_sel_hi:[1,0]
	v_cvt_pk_bf16_f32 v115, v122, v123
	global_store_dwordx2 v131, v[108:109], s[98:99]
	global_store_dwordx2 v131, v[110:111], s[98:99] offset:512
	global_store_dwordx2 v131, v[112:113], s[98:99] offset:1024
	global_store_dwordx2 v131, v[114:115], s[98:99] offset:1536
	v_add_u32_e32 v131, 0x400000, v131
	v_add_u32_e32 v126, -1, v125
	v_fma_f32 v116, -v126, v125, v124
	v_cmp_ge_f32_e32 vcc, 0, v116
	v_add_u32_e32 v117, 1, v125
	v_cndmask_b32_e32 v126, v125, v126, vcc
	v_fma_f32 v116, -v117, v125, v124
	v_cmp_lt_f32_e32 vcc, 0, v116
	s_nop 1
	v_cndmask_b32_e32 v125, v126, v117, vcc
	v_add_u32_e32 v129, -1, v128
	v_fma_f32 v118, -v129, v128, v127
	v_cmp_ge_f32_e32 vcc, 0, v118
	v_add_u32_e32 v119, 1, v128
	v_cndmask_b32_e32 v129, v128, v129, vcc
	v_fma_f32 v118, -v119, v128, v127
	v_cmp_lt_f32_e32 vcc, 0, v118
	s_nop 1
	v_cndmask_b32_e32 v128, v129, v119, vcc
	s_mov_b64 exec, 1
	global_store_dword v132, v125, s[98:99]
	v_add_u32_e32 v132, 0x2000, v132
	global_store_dword v132, v128, s[98:99]
	v_add_u32_e32 v132, 0x2000, v132
	s_mov_b64 exec, -1
	s_branch .LBB0_79
